# attention: next-tile K/V loads split into two bursts (tile top / softmax head)
# baseline (speedup 1.0000x reference)
.LBB0_796:
	s_cmp_ge_u32 s53, s26
	s_cbranch_scc1 .Lkv_skip
	s_add_i32 s7, s69, s23
	s_add_i32 s7, s7, 1
	s_lshl_b32 s7, s7, 6
	s_add_i32 s7, s7, s28
	s_add_i32 s14, s60, s68
	s_cmp_lt_u32 s53, s25
	s_cselect_b64 s[12:13], -1, 0
	s_cselect_b32 s14, s7, s14
	s_cselect_b32 s16, s29, s35
	v_add_u32_e32 v225, s14, v235
	v_med3_i32 v228, v225, 0, v237
	v_cndmask_b32_e64 v228, v225, v228, s[12:13]
	v_add_u32_e32 v228, s16, v228
	v_ashrrev_i32_e32 v229, 31, v228
	v_lshlrev_b64 v[228:229], 9, v[228:229]
	v_or_b32_e32 v228, v228, v236
	v_lshl_add_u64 v[230:231], s[46:47], 0, v[228:229]
	v_lshl_add_u64 v[228:229], s[48:49], 0, v[228:229]
	global_load_dwordx4 v[130:133], v[230:231], off
	global_load_dwordx4 v[134:137], v[230:231], off offset:256
	global_load_dwordx4 v[138:141], v[228:229], off
	global_load_dwordx4 v[142:145], v[228:229], off offset:256
; #define LAS __attribute__((address_space(3)))
; __device__ __forceinline__ void attn_mfma(LAS unsigned char* lds, int layer, int G, const int wave_s) {
;     ...
;             { const LAS unsigned char* Ks = lds + bf * AT_BUF + kv * 16384;
; #pragma unroll
;               for (int d0 = 0; d0 < 8; ++d0) { const int cb = (d0 * 16 + hi * 8) * 2;
;                   const bf16x8 k0f = *(const LAS bf16x8*)(Ks + AT_KSWZ(r32, cb)), k1f = *(const LAS bf16x8*)(Ks + AT_KSWZ(32 + r32, cb));
;                   p0 = __builtin_amdgcn_mfma_f32_32x32x16_bf16(k0f, qr[d0], p0, 0, 0, 0);
;                   p1 = __builtin_amdgcn_mfma_f32_32x32x16_bf16(k1f, qr[d0], p1, 0, 0, 0); } }
;             if (i < nw) { const int kb = AT_KEY0(i) + 4 * hi - (q0 + r32);
; #pragma unroll
;                 for (int r = 0; r < 16; ++r) { const int d = kb + (r & 3) + 8 * (r >> 2), kk = d + q0 + r32;
;                     if (d < -WINDOW || d > WINDOW || kk < 0) p0[r] = -1.0e30f;
;                     if (d + 32 < -WINDOW || d + 32 > WINDOW || kk + 32 > SEQ - 1 || kk + 32 < 0) p1[r] = -1.0e30f;
;                     if (kk > SEQ - 1) p0[r] = -1.0e30f; } }
.Lkv_skip:
	s_and_b32 s71, s17, 0x10000
	v_add_u32_e32 v0, s71, v188
	v_add_u32_e32 v199, v0, v200
	v_add_u32_e32 v222, v0, v202
	v_add_u32_e32 v239, v0, v203
	ds_read_b128 v[66:69], v199
	ds_read_b128 v[82:85], v199 offset:8192
	ds_read_b128 v[240:243], v222
	ds_read_b128 v[218:221], v222 offset:8192
	ds_read_b128 v[248:251], v239
	v_add_u32_e32 v244, v0, v204
	v_add_u32_e32 v246, v0, v205
	v_add_u32_e32 v247, v0, v206
	v_add_u32_e32 v252, v0, v207
	v_add_u32_e32 v171, v0, v208
	s_add_i32 s42, s53, -1
	s_cmp_lt_u32 s42, s25
	s_waitcnt lgkmcnt(4)
	v_mfma_f32_32x32x16_bf16 v[66:81], v[66:69], v[98:101], 0
	s_waitcnt lgkmcnt(3)
	v_mfma_f32_32x32x16_bf16 v[82:97], v[82:85], v[98:101], 0
	s_waitcnt lgkmcnt(2)
	v_mfma_f32_32x32x16_bf16 v[66:81], v[240:243], v[102:105], v[66:81]
	ds_read_b128 v[240:243], v239 offset:8192
	s_waitcnt lgkmcnt(2)
	v_mfma_f32_32x32x16_bf16 v[82:97], v[218:221], v[102:105], v[82:97]
	ds_read_b128 v[218:221], v244
	s_waitcnt lgkmcnt(2)
	v_mfma_f32_32x32x16_bf16 v[66:81], v[248:251], v[106:109], v[66:81]
	ds_read_b128 v[248:251], v244 offset:8192
	s_waitcnt lgkmcnt(2)
	v_mfma_f32_32x32x16_bf16 v[82:97], v[240:243], v[106:109], v[82:97]
	ds_read_b128 v[240:243], v246
	s_waitcnt lgkmcnt(2)
	v_mfma_f32_32x32x16_bf16 v[66:81], v[218:221], v[110:113], v[66:81]
	ds_read_b128 v[218:221], v246 offset:8192
	s_waitcnt lgkmcnt(2)
	v_mfma_f32_32x32x16_bf16 v[82:97], v[248:251], v[110:113], v[82:97]
	ds_read_b128 v[248:251], v247
	s_waitcnt lgkmcnt(2)
	v_mfma_f32_32x32x16_bf16 v[66:81], v[240:243], v[114:117], v[66:81]
	ds_read_b128 v[240:243], v247 offset:8192
	s_waitcnt lgkmcnt(2)
	v_mfma_f32_32x32x16_bf16 v[82:97], v[218:221], v[114:117], v[82:97]
	ds_read_b128 v[218:221], v252
	s_waitcnt lgkmcnt(2)
	v_mfma_f32_32x32x16_bf16 v[66:81], v[248:251], v[118:121], v[66:81]
	ds_read_b128 v[248:251], v252 offset:8192
	s_waitcnt lgkmcnt(2)
	v_mfma_f32_32x32x16_bf16 v[82:97], v[240:243], v[118:121], v[82:97]
	ds_read_b128 v[240:243], v171
	s_waitcnt lgkmcnt(2)
	v_mfma_f32_32x32x16_bf16 v[66:81], v[218:221], v[122:125], v[66:81]
	ds_read_b128 v[218:221], v171 offset:8192
	s_waitcnt lgkmcnt(2)
	v_mfma_f32_32x32x16_bf16 v[82:97], v[248:251], v[122:125], v[82:97]
	s_waitcnt lgkmcnt(1)
	v_mfma_f32_32x32x16_bf16 v[66:81], v[240:243], v[126:129], v[66:81]
	s_waitcnt lgkmcnt(0)
	v_mfma_f32_32x32x16_bf16 v[82:97], v[218:221], v[126:129], v[82:97]
	s_cbranch_scc0 .LBB0_798
	v_add_u32_e32 v218, s68, v214
	v_add_u32_e32 v0, s68, v215
	v_sub_u32_e32 v199, 0, v218
	v_sub_u32_e32 v219, 0x80, v0
	v_max_i32_e32 v199, v199, v219
	v_sub_u32_e32 v218, 0x100, v218
	v_sub_u32_e32 v0, 0x107f, v0
	v_min_i32_e32 v218, v218, v0
	v_sub_u32_e32 v218, v218, v199
	v_mov_b32_e32 v0, 0x100000
	v_cmp_gt_i32_e32 vcc, 0, v218
	s_nop 1
	v_cndmask_b32_e64 v218, v218, 0, vcc
	v_cndmask_b32_e32 v199, v199, v0, vcc
	v_sub_u32_e32 v0, 0, v199
	v_sub_u32_e32 v219, 32, v199
	v_sub_u32_e32 v220, 1, v199
	v_sub_u32_e32 v221, 33, v199
	v_cmp_gt_u32_e64 vcc, v0, v218
	v_cmp_gt_u32_e64 s[42:43], v219, v218
	v_cmp_gt_u32_e64 s[54:55], v220, v218
	v_cmp_gt_u32_e64 s[62:63], v221, v218
	v_cndmask_b32_e64 v66, v66, v238, vcc
	v_cndmask_b32_e64 v82, v82, v238, s[42:43]
	v_cndmask_b32_e64 v67, v67, v238, s[54:55]
	v_cndmask_b32_e64 v83, v83, v238, s[62:63]
	v_sub_u32_e32 v0, 2, v199
	v_sub_u32_e32 v219, 34, v199
	v_sub_u32_e32 v220, 3, v199
	v_sub_u32_e32 v221, 35, v199
	v_cmp_gt_u32_e64 vcc, v0, v218
	v_cmp_gt_u32_e64 s[42:43], v219, v218
	v_cmp_gt_u32_e64 s[54:55], v220, v218
	v_cmp_gt_u32_e64 s[62:63], v221, v218
	v_cndmask_b32_e64 v68, v68, v238, vcc
	v_cndmask_b32_e64 v84, v84, v238, s[42:43]
	v_cndmask_b32_e64 v69, v69, v238, s[54:55]
	v_cndmask_b32_e64 v85, v85, v238, s[62:63]
	v_sub_u32_e32 v0, 8, v199
	v_sub_u32_e32 v219, 40, v199
	v_sub_u32_e32 v220, 9, v199
	v_sub_u32_e32 v221, 41, v199
	v_cmp_gt_u32_e64 vcc, v0, v218
	v_cmp_gt_u32_e64 s[42:43], v219, v218
	v_cmp_gt_u32_e64 s[54:55], v220, v218
	v_cmp_gt_u32_e64 s[62:63], v221, v218
	v_cndmask_b32_e64 v70, v70, v238, vcc
	v_cndmask_b32_e64 v86, v86, v238, s[42:43]
	v_cndmask_b32_e64 v71, v71, v238, s[54:55]
	v_cndmask_b32_e64 v87, v87, v238, s[62:63]
	v_sub_u32_e32 v0, 10, v199
	v_sub_u32_e32 v219, 42, v199
	v_sub_u32_e32 v220, 11, v199
	v_sub_u32_e32 v221, 43, v199
	v_cmp_gt_u32_e64 vcc, v0, v218
	v_cmp_gt_u32_e64 s[42:43], v219, v218
	v_cmp_gt_u32_e64 s[54:55], v220, v218
	v_cmp_gt_u32_e64 s[62:63], v221, v218
	v_cndmask_b32_e64 v72, v72, v238, vcc
	v_cndmask_b32_e64 v88, v88, v238, s[42:43]
	v_cndmask_b32_e64 v73, v73, v238, s[54:55]
	v_cndmask_b32_e64 v89, v89, v238, s[62:63]
	v_sub_u32_e32 v0, 16, v199
	v_sub_u32_e32 v219, 48, v199
	v_sub_u32_e32 v220, 17, v199
	v_sub_u32_e32 v221, 49, v199
	v_cmp_gt_u32_e64 vcc, v0, v218
	v_cmp_gt_u32_e64 s[42:43], v219, v218
	v_cmp_gt_u32_e64 s[54:55], v220, v218
	v_cmp_gt_u32_e64 s[62:63], v221, v218
	v_cndmask_b32_e64 v74, v74, v238, vcc
	v_cndmask_b32_e64 v90, v90, v238, s[42:43]
	v_cndmask_b32_e64 v75, v75, v238, s[54:55]
	v_cndmask_b32_e64 v91, v91, v238, s[62:63]
	v_sub_u32_e32 v0, 18, v199
	v_sub_u32_e32 v219, 50, v199
	v_sub_u32_e32 v220, 19, v199
	v_sub_u32_e32 v221, 51, v199
	v_cmp_gt_u32_e64 vcc, v0, v218
	v_cmp_gt_u32_e64 s[42:43], v219, v218
	v_cmp_gt_u32_e64 s[54:55], v220, v218
	v_cmp_gt_u32_e64 s[62:63], v221, v218
	v_cndmask_b32_e64 v76, v76, v238, vcc
	v_cndmask_b32_e64 v92, v92, v238, s[42:43]
	v_cndmask_b32_e64 v77, v77, v238, s[54:55]
	v_cndmask_b32_e64 v93, v93, v238, s[62:63]
	v_sub_u32_e32 v0, 24, v199
	v_sub_u32_e32 v219, 56, v199
	v_sub_u32_e32 v220, 25, v199
	v_sub_u32_e32 v221, 57, v199
	v_cmp_gt_u32_e64 vcc, v0, v218
	v_cmp_gt_u32_e64 s[42:43], v219, v218
	v_cmp_gt_u32_e64 s[54:55], v220, v218
	v_cmp_gt_u32_e64 s[62:63], v221, v218
	v_cndmask_b32_e64 v78, v78, v238, vcc
	v_cndmask_b32_e64 v94, v94, v238, s[42:43]
	v_cndmask_b32_e64 v79, v79, v238, s[54:55]
	v_cndmask_b32_e64 v95, v95, v238, s[62:63]
	v_sub_u32_e32 v0, 26, v199
	v_sub_u32_e32 v219, 58, v199
	v_sub_u32_e32 v220, 27, v199
	v_sub_u32_e32 v221, 59, v199
	v_cmp_gt_u32_e64 vcc, v0, v218
	v_cmp_gt_u32_e64 s[42:43], v219, v218
	v_cmp_gt_u32_e64 s[54:55], v220, v218
	v_cmp_gt_u32_e64 s[62:63], v221, v218
	v_cndmask_b32_e64 v80, v80, v238, vcc
	v_cndmask_b32_e64 v96, v96, v238, s[42:43]
	v_cndmask_b32_e64 v81, v81, v238, s[54:55]
	v_cndmask_b32_e64 v97, v97, v238, s[62:63]
.LBB0_798:
	s_cmp_ge_u32 s53, s26
	s_cbranch_scc1 .Lkv_skip2
	v_add_u32_e32 v228, 32, v225
	v_med3_i32 v229, v228, 0, v237
	v_cndmask_b32_e64 v228, v228, v229, s[12:13]
	v_add_u32_e32 v228, s16, v228
	v_ashrrev_i32_e32 v229, 31, v228
	v_lshlrev_b64 v[228:229], 9, v[228:229]
	v_or_b32_e32 v228, v228, v236
	v_lshl_add_u64 v[230:231], s[46:47], 0, v[228:229]
	v_lshl_add_u64 v[228:229], s[48:49], 0, v[228:229]
	global_load_dwordx4 v[146:149], v[230:231], off
	global_load_dwordx4 v[150:153], v[230:231], off offset:256
	global_load_dwordx4 v[154:157], v[228:229], off
	global_load_dwordx4 v[158:161], v[228:229], off offset:256
